# hand-written grid barrier at 17 sites: last XCD leader releases all XCD generation words directly (one poll hop less), global_ instead of flat_ ops
# speedup vs baseline: 1.0058x; 1.0058x over previous
_Z10hybrid_fwd4Args:
	s_mov_b64 s[92:93], s[0:1]
	s_mov_b32 s98, 0
	s_load_dword s90, s[0:1], 0xf8
	s_load_dwordx2 s[88:89], s[0:1], 0xf0
	v_readfirstlane_b32 s0, v0
	s_nop 1
	v_writelane_b32 v254, s0, 0
	s_add_u32 s0, s92, 0xf8
	s_addc_u32 s1, s93, 0
	v_writelane_b32 v254, s0, 1
	s_nop 1
	v_writelane_b32 v254, s1, 2
	s_waitcnt lgkmcnt(0)
	s_and_b32 s0, s90, 7
	v_writelane_b32 v254, s2, 3
	s_cmp_lg_u32 s0, 0
	v_writelane_b32 v254, s2, 4
	s_cbranch_scc1 .LBB0_2
	v_readlane_b32 s3, v254, 3
	s_ashr_i32 s1, s3, 31
	s_lshr_b32 s1, s1, 29
	s_add_i32 s1, s3, s1
	s_ashr_i32 s2, s1, 3
	s_and_b32 s1, s1, -8
	s_ashr_i32 s0, s90, 3
	s_sub_i32 s1, s3, s1
	s_mul_i32 s0, s0, s1
	s_add_i32 s0, s0, s2
	v_writelane_b32 v254, s0, 4

.LBB0_99:
	s_or_b64 exec, exec, s[0:1]
	s_waitcnt lgkmcnt(0)
	s_barrier
	s_add_u32 s98, s98, 1

.LBB0_142:
	s_cmp_lt_i32 s89, 3
	s_cbranch_scc1 .LBB0_188
	s_waitcnt vmcnt(0) lgkmcnt(0)
	s_barrier
	v_readlane_b32 s0, v254, 0
	v_readlane_b32 s4, v254, 6
	v_readlane_b32 s5, v254, 5
	s_andn2_b32 s0, s0, 63
	s_cmp_lg_u32 s0, 0
	s_cbranch_scc1 .Lnb_end_1
	s_mov_b64 s[2:3], exec
	s_mov_b64 exec, 1
	v_mov_b32_e32 v0, s4
	v_mov_b32_e32 v4, 1
	v_mov_b32_e32 v5, 0
	ds_read_b64 v[2:3], v0
	s_lshl_b32 s6, s5, 8
	s_add_u32 s8, s84, s6
	s_addc_u32 s9, s85, 0
	s_add_u32 s16, s8, 0x2400
	s_addc_u32 s17, s9, 0
	s_add_u32 s8, s8, 0x1400
	s_addc_u32 s9, s9, 0
	s_add_u32 s20, s84, 0x3400
	s_addc_u32 s21, s85, 0
	s_add_u32 s26, s84, 0x2400
	s_addc_u32 s27, s85, 0
	s_mov_b32 s24, 0
	global_atomic_add v6, v5, v4, s[8:9] sc0
	s_add_u32 s13, s98, 1
	s_waitcnt vmcnt(0) lgkmcnt(0)
	v_readfirstlane_b32 s10, v6
	v_readfirstlane_b32 s11, v2
	v_readfirstlane_b32 s12, v3
	s_add_u32 s10, s10, 1
	s_mul_i32 s14, s13, s11
	s_cmp_eq_u32 s10, s14
	s_cbranch_scc1 .Lnb_leader_1
.Lnb_spin_1:
	s_sleep 1
	global_load_dword v7, v5, s[16:17] sc1
	s_waitcnt vmcnt(0)
	v_readfirstlane_b32 s18, v7
	s_cmp_lg_u32 s18, s98
	s_cbranch_scc1 .Lnb_acq_1
	s_add_u32 s24, s24, 1
	s_and_b32 s25, s24, 0xff
	s_cmp_lg_u32 s25, 0
	s_cbranch_scc1 .Lnb_spin_1
	global_load_dword v9, v5, s[84:85] offset:512 sc1
	s_waitcnt vmcnt(0)
	v_readfirstlane_b32 s25, v9
	s_cmp_lg_u32 s25, 0
	s_cbranch_scc1 .Lnb_acq_1
	s_cmp_lt_u32 s24, 0x40001
	s_cbranch_scc1 .Lnb_spin_1
	global_atomic_add v5, v4, s[84:85] offset:512
	s_branch .Lnb_acq_1
.Lnb_leader_1:
	buffer_wbl2 sc1
	s_waitcnt vmcnt(0)
	global_atomic_add v8, v5, v4, s[20:21] sc0
	s_mul_i32 s23, s13, s12
	s_waitcnt vmcnt(0)
	v_readfirstlane_b32 s22, v8
	s_add_u32 s22, s22, 1
	s_cmp_eq_u32 s22, s23
	s_cbranch_scc0 .Lnb_spin_1
	global_atomic_add v5, v4, s[26:27] offset:0
	global_atomic_add v5, v4, s[26:27] offset:256
	global_atomic_add v5, v4, s[26:27] offset:512
	global_atomic_add v5, v4, s[26:27] offset:768
	global_atomic_add v5, v4, s[26:27] offset:1024
	global_atomic_add v5, v4, s[26:27] offset:1280
	global_atomic_add v5, v4, s[26:27] offset:1536
	global_atomic_add v5, v4, s[26:27] offset:1792
	global_atomic_add v5, v4, s[26:27] offset:2048
	global_atomic_add v5, v4, s[26:27] offset:2304
	global_atomic_add v5, v4, s[26:27] offset:2560
	global_atomic_add v5, v4, s[26:27] offset:2816
	global_atomic_add v5, v4, s[26:27] offset:3072
	global_atomic_add v5, v4, s[26:27] offset:3328
	global_atomic_add v5, v4, s[26:27] offset:3584
	global_atomic_add v5, v4, s[26:27] offset:3840
.Lnb_acq_1:
	buffer_inv sc1
	s_waitcnt vmcnt(0)
	s_mov_b64 exec, s[2:3]
.Lnb_end_1:
	s_add_u32 s98, s98, 1
	s_barrier

.LBB0_512:
	s_cmp_lt_i32 s89, 4
	s_cbranch_scc1 .LBB0_558
	s_waitcnt vmcnt(0) lgkmcnt(0)
	s_barrier
	v_readlane_b32 s0, v254, 0
	v_readlane_b32 s4, v254, 6
	v_readlane_b32 s5, v254, 5
	s_andn2_b32 s0, s0, 63
	s_cmp_lg_u32 s0, 0
	s_cbranch_scc1 .Lnb_end_2
	s_mov_b64 s[2:3], exec
	s_mov_b64 exec, 1
	v_mov_b32_e32 v0, s4
	v_mov_b32_e32 v4, 1
	v_mov_b32_e32 v5, 0
	ds_read_b64 v[2:3], v0
	s_lshl_b32 s6, s5, 8
	s_add_u32 s8, s84, s6
	s_addc_u32 s9, s85, 0
	s_add_u32 s16, s8, 0x2400
	s_addc_u32 s17, s9, 0
	s_add_u32 s8, s8, 0x1400
	s_addc_u32 s9, s9, 0
	s_add_u32 s20, s84, 0x3400
	s_addc_u32 s21, s85, 0
	s_add_u32 s26, s84, 0x2400
	s_addc_u32 s27, s85, 0
	s_mov_b32 s24, 0
	global_atomic_add v6, v5, v4, s[8:9] sc0
	s_add_u32 s13, s98, 1
	s_waitcnt vmcnt(0) lgkmcnt(0)
	v_readfirstlane_b32 s10, v6
	v_readfirstlane_b32 s11, v2
	v_readfirstlane_b32 s12, v3
	s_add_u32 s10, s10, 1
	s_mul_i32 s14, s13, s11
	s_cmp_eq_u32 s10, s14
	s_cbranch_scc1 .Lnb_leader_2

.LBB0_857:
	s_cmp_lt_i32 s89, 5
	s_barrier
	s_cbranch_scc1 .LBB0_906
	s_waitcnt vmcnt(0) lgkmcnt(0)
	s_barrier
	v_readlane_b32 s0, v254, 0
	v_readlane_b32 s4, v254, 6
	v_readlane_b32 s5, v254, 5
	s_andn2_b32 s0, s0, 63
	s_cmp_lg_u32 s0, 0
	s_cbranch_scc1 .Lnb_end_3
	s_mov_b64 s[2:3], exec
	s_mov_b64 exec, 1
	v_mov_b32_e32 v0, s4
	v_mov_b32_e32 v4, 1
	v_mov_b32_e32 v5, 0
	ds_read_b64 v[2:3], v0
	s_lshl_b32 s6, s5, 8
	s_add_u32 s8, s84, s6
	s_addc_u32 s9, s85, 0
	s_add_u32 s16, s8, 0x2400
	s_addc_u32 s17, s9, 0
	s_add_u32 s8, s8, 0x1400
	s_addc_u32 s9, s9, 0
	s_add_u32 s20, s84, 0x3400
	s_addc_u32 s21, s85, 0
	s_add_u32 s26, s84, 0x2400
	s_addc_u32 s27, s85, 0
	s_mov_b32 s24, 0
	global_atomic_add v6, v5, v4, s[8:9] sc0
	s_add_u32 s13, s98, 1
	s_waitcnt vmcnt(0) lgkmcnt(0)
	v_readfirstlane_b32 s10, v6
	v_readfirstlane_b32 s11, v2
	v_readfirstlane_b32 s12, v3
	s_add_u32 s10, s10, 1
	s_mul_i32 s14, s13, s11
	s_cmp_eq_u32 s10, s14
	s_cbranch_scc1 .Lnb_leader_3

.Lnb_end_3:
	s_add_u32 s98, s98, 1
	s_barrier
	s_branch .LBB0_906

.LBB0_871:
.LBB0_872:
	s_and_b32 s0, s26, 0xffffffe0
	s_lshl_b32 s1, s27, 3
	s_add_i32 s0, s0, s1
	s_sub_i32 s2, s0, 48
	s_movk_i32 s4, 0x100
	s_movk_i32 s6, 0x258
	s_movk_i32 s5, 0x348
	s_cbranch_execz .LBB0_839
	s_branch .LBB0_840
.LBB0_906:
	s_cmp_lt_i32 s88, 5
	s_cselect_b64 s[0:1], -1, 0
	s_cmp_gt_i32 s89, 4
	s_cselect_b64 s[2:3], -1, 0
	s_and_b64 s[0:1], s[0:1], s[2:3]
	s_andn2_b64 vcc, exec, s[0:1]
	s_cbranch_vccnz .LBB0_979
	v_readlane_b32 s0, v254, 0
	v_mbcnt_lo_u32_b32 v0, -1, 0
	s_andn2_b32 s0, s0, 63
	v_mbcnt_hi_u32_b32 v32, -1, v0
	v_or_b32_e32 v30, s0, v32
	s_mov_b32 s22, s90
	v_readlane_b32 s2, v254, 3
	s_mov_b64 s[0:1], s[92:93]
	v_readlane_b32 s23, v254, 4
	v_mov_b32_e32 v31, 0
	s_load_dwordx2 s[4:5], s[0:1], 0xe8
	s_mov_b32 s7, 0
	v_mov_b32_e32 v25, 0
	s_cmpk_gt_i32 s23, 0x3ff
	v_xor_b32_e32 v34, 16, v32
	v_and_b32_e32 v35, 64, v32
	v_xor_b32_e32 v33, 32, v32
	s_cbranch_scc1 .LBB0_920
	s_waitcnt lgkmcnt(0)
	s_add_u32 s24, s4, 0x10000000
	s_addc_u32 s25, s5, 0
	v_add_u32_e32 v0, 64, v35
	s_add_u32 s26, s4, 0x16100000
	v_cmp_lt_i32_e32 vcc, v34, v0
	s_addc_u32 s27, s5, 0
	s_add_u32 s8, s4, 0xb00000
	v_cndmask_b32_e32 v1, v32, v34, vcc
	v_cmp_lt_i32_e32 vcc, v33, v0
	s_addc_u32 s9, s5, 0
	v_lshlrev_b32_e32 v36, 2, v1
	v_cndmask_b32_e32 v0, v32, v33, vcc
	v_lshlrev_b32_e32 v37, 2, v0
	s_mov_b64 s[10:11], 0x10000
	s_mov_b64 s[12:13], 0x10400
	s_mov_b64 s[14:15], 0x14000
	s_movk_i32 s28, 0x1c00
	v_mov_b64_e32 v[26:27], s[4:5]
	s_mov_b64 s[16:17], 0x2e00c00
	s_mov_b32 s29, 0x2e00000
	s_mov_b32 s30, 0xc000
	v_mov_b32_e32 v38, 0x358637bd
	s_mov_b32 s31, 0x800000
	s_mov_b32 s33, s23
	s_branch .LBB0_910

.LBB0_933:
	s_cmp_lt_i32 s89, 6
	s_cbranch_scc1 .LBB0_979
	s_waitcnt vmcnt(0) lgkmcnt(0)
	s_barrier
	v_readlane_b32 s0, v254, 0
	v_readlane_b32 s4, v254, 6
	v_readlane_b32 s5, v254, 5
	s_andn2_b32 s0, s0, 63
	s_cmp_lg_u32 s0, 0
	s_cbranch_scc1 .Lnb_end_4
	s_mov_b64 s[2:3], exec
	s_mov_b64 exec, 1
	v_mov_b32_e32 v0, s4
	v_mov_b32_e32 v4, 1
	v_mov_b32_e32 v5, 0
	ds_read_b64 v[2:3], v0
	s_lshl_b32 s6, s5, 8
	s_add_u32 s8, s84, s6
	s_addc_u32 s9, s85, 0
	s_add_u32 s16, s8, 0x2400
	s_addc_u32 s17, s9, 0
	s_add_u32 s8, s8, 0x1400
	s_addc_u32 s9, s9, 0
	s_add_u32 s20, s84, 0x3400
	s_addc_u32 s21, s85, 0
	s_add_u32 s26, s84, 0x2400
	s_addc_u32 s27, s85, 0
	s_mov_b32 s24, 0
	global_atomic_add v6, v5, v4, s[8:9] sc0
	s_add_u32 s13, s98, 1
	s_waitcnt vmcnt(0) lgkmcnt(0)
	v_readfirstlane_b32 s10, v6
	v_readfirstlane_b32 s11, v2
	v_readfirstlane_b32 s12, v3
	s_add_u32 s10, s10, 1
	s_mul_i32 s14, s13, s11
	s_cmp_eq_u32 s10, s14
	s_cbranch_scc1 .Lnb_leader_4

.LBB0_1175:
	s_cmp_lt_i32 s89, 7
	s_cbranch_scc1 .LBB0_1221
	s_waitcnt vmcnt(0) lgkmcnt(0)
	s_barrier
	v_readlane_b32 s0, v254, 0
	v_readlane_b32 s4, v254, 6
	v_readlane_b32 s5, v254, 5
	s_andn2_b32 s0, s0, 63
	s_cmp_lg_u32 s0, 0
	s_cbranch_scc1 .Lnb_end_5
	s_mov_b64 s[2:3], exec
	s_mov_b64 exec, 1
	v_mov_b32_e32 v0, s4
	v_mov_b32_e32 v4, 1
	v_mov_b32_e32 v5, 0
	ds_read_b64 v[2:3], v0
	s_lshl_b32 s6, s5, 8
	s_add_u32 s8, s84, s6
	s_addc_u32 s9, s85, 0
	s_add_u32 s16, s8, 0x2400
	s_addc_u32 s17, s9, 0
	s_add_u32 s8, s8, 0x1400
	s_addc_u32 s9, s9, 0
	s_add_u32 s20, s84, 0x3400
	s_addc_u32 s21, s85, 0
	s_add_u32 s26, s84, 0x2400
	s_addc_u32 s27, s85, 0
	s_mov_b32 s24, 0
	global_atomic_add v6, v5, v4, s[8:9] sc0
	s_add_u32 s13, s98, 1
	s_waitcnt vmcnt(0) lgkmcnt(0)
	v_readfirstlane_b32 s10, v6
	v_readfirstlane_b32 s11, v2
	v_readfirstlane_b32 s12, v3
	s_add_u32 s10, s10, 1
	s_mul_i32 s14, s13, s11
	s_cmp_eq_u32 s10, s14
	s_cbranch_scc1 .Lnb_leader_5

.LBB0_1237:
	s_cmp_lt_i32 s89, 8
	s_barrier
	s_cbranch_scc1 .LBB0_1283
	s_waitcnt vmcnt(0) lgkmcnt(0)
	s_barrier
	v_readlane_b32 s0, v254, 0
	v_readlane_b32 s4, v254, 6
	v_readlane_b32 s5, v254, 5
	s_andn2_b32 s0, s0, 63
	s_cmp_lg_u32 s0, 0
	s_cbranch_scc1 .Lnb_end_6
	s_mov_b64 s[2:3], exec
	s_mov_b64 exec, 1
	v_mov_b32_e32 v0, s4
	v_mov_b32_e32 v4, 1
	v_mov_b32_e32 v5, 0
	ds_read_b64 v[2:3], v0
	s_lshl_b32 s6, s5, 8
	s_add_u32 s8, s84, s6
	s_addc_u32 s9, s85, 0
	s_add_u32 s16, s8, 0x2400
	s_addc_u32 s17, s9, 0
	s_add_u32 s8, s8, 0x1400
	s_addc_u32 s9, s9, 0
	s_add_u32 s20, s84, 0x3400
	s_addc_u32 s21, s85, 0
	s_add_u32 s26, s84, 0x2400
	s_addc_u32 s27, s85, 0
	s_mov_b32 s24, 0
	global_atomic_add v6, v5, v4, s[8:9] sc0
	s_add_u32 s13, s98, 1
	s_waitcnt vmcnt(0) lgkmcnt(0)
	v_readfirstlane_b32 s10, v6
	v_readfirstlane_b32 s11, v2
	v_readfirstlane_b32 s12, v3
	s_add_u32 s10, s10, 1
	s_mul_i32 s14, s13, s11
	s_cmp_eq_u32 s10, s14
	s_cbranch_scc1 .Lnb_leader_6

.LBB0_1308:
	s_cmp_lt_i32 s89, 9
	s_cbranch_scc1 .LBB0_1354
	s_waitcnt vmcnt(0) lgkmcnt(0)
	s_barrier
	v_readlane_b32 s0, v254, 0
	v_readlane_b32 s4, v254, 6
	v_readlane_b32 s5, v254, 5
	s_andn2_b32 s0, s0, 63
	s_cmp_lg_u32 s0, 0
	s_cbranch_scc1 .Lnb_end_7
	s_mov_b64 s[2:3], exec
	s_mov_b64 exec, 1
	v_mov_b32_e32 v0, s4
	v_mov_b32_e32 v4, 1
	v_mov_b32_e32 v5, 0
	ds_read_b64 v[2:3], v0
	s_lshl_b32 s6, s5, 8
	s_add_u32 s8, s84, s6
	s_addc_u32 s9, s85, 0
	s_add_u32 s16, s8, 0x2400
	s_addc_u32 s17, s9, 0
	s_add_u32 s8, s8, 0x1400
	s_addc_u32 s9, s9, 0
	s_add_u32 s20, s84, 0x3400
	s_addc_u32 s21, s85, 0
	s_add_u32 s26, s84, 0x2400
	s_addc_u32 s27, s85, 0
	s_mov_b32 s24, 0
	global_atomic_add v6, v5, v4, s[8:9] sc0
	s_add_u32 s13, s98, 1
	s_waitcnt vmcnt(0) lgkmcnt(0)
	v_readfirstlane_b32 s10, v6
	v_readfirstlane_b32 s11, v2
	v_readfirstlane_b32 s12, v3
	s_add_u32 s10, s10, 1
	s_mul_i32 s14, s13, s11
	s_cmp_eq_u32 s10, s14
	s_cbranch_scc1 .Lnb_leader_7

.LBB0_1481:
	s_cmp_lt_i32 s89, 10
	s_cbranch_scc1 .LBB0_1527
	s_waitcnt vmcnt(0) lgkmcnt(0)
	s_barrier
	v_readlane_b32 s0, v254, 0
	v_readlane_b32 s4, v254, 6
	v_readlane_b32 s5, v254, 5
	s_andn2_b32 s0, s0, 63
	s_cmp_lg_u32 s0, 0
	s_cbranch_scc1 .Lnb_end_8
	s_mov_b64 s[2:3], exec
	s_mov_b64 exec, 1
	v_mov_b32_e32 v0, s4
	v_mov_b32_e32 v4, 1
	v_mov_b32_e32 v5, 0
	ds_read_b64 v[2:3], v0
	s_lshl_b32 s6, s5, 8
	s_add_u32 s8, s84, s6
	s_addc_u32 s9, s85, 0
	s_add_u32 s16, s8, 0x2400
	s_addc_u32 s17, s9, 0
	s_add_u32 s8, s8, 0x1400
	s_addc_u32 s9, s9, 0
	s_add_u32 s20, s84, 0x3400
	s_addc_u32 s21, s85, 0
	s_add_u32 s26, s84, 0x2400
	s_addc_u32 s27, s85, 0
	s_mov_b32 s24, 0
	global_atomic_add v6, v5, v4, s[8:9] sc0
	s_add_u32 s13, s98, 1
	s_waitcnt vmcnt(0) lgkmcnt(0)
	v_readfirstlane_b32 s10, v6
	v_readfirstlane_b32 s11, v2
	v_readfirstlane_b32 s12, v3
	s_add_u32 s10, s10, 1
	s_mul_i32 s14, s13, s11
	s_cmp_eq_u32 s10, s14
	s_cbranch_scc1 .Lnb_leader_8

.LBB0_1563:
	s_cmp_lt_i32 s89, 11
	s_barrier
	s_cbranch_scc1 .LBB0_1609
	s_waitcnt vmcnt(0) lgkmcnt(0)
	s_barrier
	v_readlane_b32 s0, v254, 0
	v_readlane_b32 s4, v254, 6
	v_readlane_b32 s5, v254, 5
	s_andn2_b32 s0, s0, 63
	s_cmp_lg_u32 s0, 0
	s_cbranch_scc1 .Lnb_end_9
	s_mov_b64 s[2:3], exec
	s_mov_b64 exec, 1
	v_mov_b32_e32 v0, s4
	v_mov_b32_e32 v4, 1
	v_mov_b32_e32 v5, 0
	ds_read_b64 v[2:3], v0
	s_lshl_b32 s6, s5, 8
	s_add_u32 s8, s84, s6
	s_addc_u32 s9, s85, 0
	s_add_u32 s16, s8, 0x2400
	s_addc_u32 s17, s9, 0
	s_add_u32 s8, s8, 0x1400
	s_addc_u32 s9, s9, 0
	s_add_u32 s20, s84, 0x3400
	s_addc_u32 s21, s85, 0
	s_add_u32 s26, s84, 0x2400
	s_addc_u32 s27, s85, 0
	s_mov_b32 s24, 0
	global_atomic_add v6, v5, v4, s[8:9] sc0
	s_add_u32 s13, s98, 1
	s_waitcnt vmcnt(0) lgkmcnt(0)
	v_readfirstlane_b32 s10, v6
	v_readfirstlane_b32 s11, v2
	v_readfirstlane_b32 s12, v3
	s_add_u32 s10, s10, 1
	s_mul_i32 s14, s13, s11
	s_cmp_eq_u32 s10, s14
	s_cbranch_scc1 .Lnb_leader_9

.LBB0_1651:
	s_cmp_lt_i32 s89, 12
	s_cbranch_scc1 .LBB0_1697
	s_waitcnt vmcnt(0) lgkmcnt(0)
	s_barrier
	v_readlane_b32 s0, v254, 0
	v_readlane_b32 s4, v254, 6
	v_readlane_b32 s5, v254, 5
	s_andn2_b32 s0, s0, 63
	s_cmp_lg_u32 s0, 0
	s_cbranch_scc1 .Lnb_end_10
	s_mov_b64 s[2:3], exec
	s_mov_b64 exec, 1
	v_mov_b32_e32 v0, s4
	v_mov_b32_e32 v4, 1
	v_mov_b32_e32 v5, 0
	ds_read_b64 v[2:3], v0
	s_lshl_b32 s6, s5, 8
	s_add_u32 s8, s84, s6
	s_addc_u32 s9, s85, 0
	s_add_u32 s16, s8, 0x2400
	s_addc_u32 s17, s9, 0
	s_add_u32 s8, s8, 0x1400
	s_addc_u32 s9, s9, 0
	s_add_u32 s20, s84, 0x3400
	s_addc_u32 s21, s85, 0
	s_add_u32 s26, s84, 0x2400
	s_addc_u32 s27, s85, 0
	s_mov_b32 s24, 0
	global_atomic_add v6, v5, v4, s[8:9] sc0
	s_add_u32 s13, s98, 1
	s_waitcnt vmcnt(0) lgkmcnt(0)
	v_readfirstlane_b32 s10, v6
	v_readfirstlane_b32 s11, v2
	v_readfirstlane_b32 s12, v3
	s_add_u32 s10, s10, 1
	s_mul_i32 s14, s13, s11
	s_cmp_eq_u32 s10, s14
	s_cbranch_scc1 .Lnb_leader_10

.LBB0_2021:
	s_cmp_lt_i32 s89, 13
	s_cbranch_scc1 .LBB0_2067
	s_waitcnt vmcnt(0) lgkmcnt(0)
	s_barrier
	v_readlane_b32 s0, v254, 0
	v_readlane_b32 s4, v254, 6
	v_readlane_b32 s5, v254, 5
	s_andn2_b32 s0, s0, 63
	s_cmp_lg_u32 s0, 0
	s_cbranch_scc1 .Lnb_end_11
	s_mov_b64 s[2:3], exec
	s_mov_b64 exec, 1
	v_mov_b32_e32 v0, s4
	v_mov_b32_e32 v4, 1
	v_mov_b32_e32 v5, 0
	ds_read_b64 v[2:3], v0
	s_lshl_b32 s6, s5, 8
	s_add_u32 s8, s84, s6
	s_addc_u32 s9, s85, 0
	s_add_u32 s16, s8, 0x2400
	s_addc_u32 s17, s9, 0
	s_add_u32 s8, s8, 0x1400
	s_addc_u32 s9, s9, 0
	s_add_u32 s20, s84, 0x3400
	s_addc_u32 s21, s85, 0
	s_add_u32 s26, s84, 0x2400
	s_addc_u32 s27, s85, 0
	s_mov_b32 s24, 0
	global_atomic_add v6, v5, v4, s[8:9] sc0
	s_add_u32 s13, s98, 1
	s_waitcnt vmcnt(0) lgkmcnt(0)
	v_readfirstlane_b32 s10, v6
	v_readfirstlane_b32 s11, v2
	v_readfirstlane_b32 s12, v3
	s_add_u32 s10, s10, 1
	s_mul_i32 s14, s13, s11
	s_cmp_eq_u32 s10, s14
	s_cbranch_scc1 .Lnb_leader_11

.LBB0_2366:
	s_cmp_lt_i32 s89, 14
	s_barrier
	s_cbranch_scc1 .LBB0_2415
	s_waitcnt vmcnt(0) lgkmcnt(0)
	s_barrier
	v_readlane_b32 s0, v254, 0
	v_readlane_b32 s4, v254, 6
	v_readlane_b32 s5, v254, 5
	s_andn2_b32 s0, s0, 63
	s_cmp_lg_u32 s0, 0
	s_cbranch_scc1 .Lnb_end_12
	s_mov_b64 s[2:3], exec
	s_mov_b64 exec, 1
	v_mov_b32_e32 v0, s4
	v_mov_b32_e32 v4, 1
	v_mov_b32_e32 v5, 0
	ds_read_b64 v[2:3], v0
	s_lshl_b32 s6, s5, 8
	s_add_u32 s8, s84, s6
	s_addc_u32 s9, s85, 0
	s_add_u32 s16, s8, 0x2400
	s_addc_u32 s17, s9, 0
	s_add_u32 s8, s8, 0x1400
	s_addc_u32 s9, s9, 0
	s_add_u32 s20, s84, 0x3400
	s_addc_u32 s21, s85, 0
	s_add_u32 s26, s84, 0x2400
	s_addc_u32 s27, s85, 0
	s_mov_b32 s24, 0
	global_atomic_add v6, v5, v4, s[8:9] sc0
	s_add_u32 s13, s98, 1
	s_waitcnt vmcnt(0) lgkmcnt(0)
	v_readfirstlane_b32 s10, v6
	v_readfirstlane_b32 s11, v2
	v_readfirstlane_b32 s12, v3
	s_add_u32 s10, s10, 1
	s_mul_i32 s14, s13, s11
	s_cmp_eq_u32 s10, s14
	s_cbranch_scc1 .Lnb_leader_12

.LBB0_2380:
.LBB0_2381:
	s_and_b32 s0, s28, 0xffffffe0
	s_lshl_b32 s1, s26, 3
	s_add_i32 s0, s0, s1
	s_sub_i32 s2, s0, 48
	s_movk_i32 s4, 0x100
	s_movk_i32 s6, 0x258
	s_movk_i32 s5, 0x348
	s_cbranch_execz .LBB0_2348
	s_branch .LBB0_2349
.LBB0_2415:
	s_cmp_lt_i32 s88, 14
	s_cselect_b64 s[0:1], -1, 0
	s_cmp_gt_i32 s89, 13
	s_cselect_b64 s[2:3], -1, 0
	s_and_b64 s[0:1], s[0:1], s[2:3]
	s_andn2_b64 vcc, exec, s[0:1]
	s_cbranch_vccnz .LBB0_2488
	v_readlane_b32 s0, v254, 0
	s_waitcnt vmcnt(0)
	v_mbcnt_lo_u32_b32 v0, -1, 0
	s_andn2_b32 s0, s0, 63
	v_mbcnt_hi_u32_b32 v32, -1, v0
	v_or_b32_e32 v30, s0, v32
	v_mov_b32_e32 v31, 0
	s_mov_b32 s22, s90
	v_readlane_b32 s2, v254, 3
	s_mov_b64 s[0:1], s[92:93]
	v_readlane_b32 s23, v254, 4
	s_waitcnt lgkmcnt(0)
	s_load_dwordx2 s[4:5], s[0:1], 0xe8
	s_mov_b32 s7, 0
	v_mov_b32_e32 v25, 0
	s_cmpk_gt_i32 s23, 0x3ff
	v_xor_b32_e32 v34, 16, v32
	v_and_b32_e32 v35, 64, v32
	v_xor_b32_e32 v33, 32, v32
	s_cbranch_scc1 .LBB0_2429
	s_waitcnt lgkmcnt(0)
	s_add_u32 s24, s4, 0x10000000
	s_addc_u32 s25, s5, 0
	v_add_u32_e32 v0, 64, v35
	s_add_u32 s26, s4, 0x16100000
	v_cmp_lt_i32_e32 vcc, v34, v0
	s_addc_u32 s27, s5, 0
	s_add_u32 s8, s4, 0xb00000
	v_cndmask_b32_e32 v1, v32, v34, vcc
	v_cmp_lt_i32_e32 vcc, v33, v0
	s_addc_u32 s9, s5, 0
	v_lshlrev_b32_e32 v36, 2, v1
	v_cndmask_b32_e32 v0, v32, v33, vcc
	v_lshlrev_b32_e32 v37, 2, v0
	s_mov_b64 s[10:11], 0x10000
	s_mov_b64 s[12:13], 0x10400
	s_mov_b64 s[14:15], 0x14000
	s_movk_i32 s28, 0x1c00
	v_mov_b64_e32 v[26:27], s[4:5]
	s_mov_b64 s[16:17], 0x2e00c00
	s_mov_b32 s29, 0x2e00000
	s_mov_b32 s30, 0xc000
	v_mov_b32_e32 v38, 0x358637bd
	s_mov_b32 s31, 0x800000
	s_mov_b32 s33, s23
	s_branch .LBB0_2419

.LBB0_2442:
	s_cmp_lt_i32 s89, 15
	s_cbranch_scc1 .LBB0_2488
	s_waitcnt vmcnt(0) lgkmcnt(0)
	s_barrier
	v_readlane_b32 s0, v254, 0
	v_readlane_b32 s4, v254, 6
	v_readlane_b32 s5, v254, 5
	s_andn2_b32 s0, s0, 63
	s_cmp_lg_u32 s0, 0
	s_cbranch_scc1 .Lnb_end_13
	s_mov_b64 s[2:3], exec
	s_mov_b64 exec, 1
	v_mov_b32_e32 v0, s4
	v_mov_b32_e32 v4, 1
	v_mov_b32_e32 v5, 0
	ds_read_b64 v[2:3], v0
	s_lshl_b32 s6, s5, 8
	s_add_u32 s8, s84, s6
	s_addc_u32 s9, s85, 0
	s_add_u32 s16, s8, 0x2400
	s_addc_u32 s17, s9, 0
	s_add_u32 s8, s8, 0x1400
	s_addc_u32 s9, s9, 0
	s_add_u32 s20, s84, 0x3400
	s_addc_u32 s21, s85, 0
	s_add_u32 s26, s84, 0x2400
	s_addc_u32 s27, s85, 0
	s_mov_b32 s24, 0
	global_atomic_add v6, v5, v4, s[8:9] sc0
	s_add_u32 s13, s98, 1
	s_waitcnt vmcnt(0) lgkmcnt(0)
	v_readfirstlane_b32 s10, v6
	v_readfirstlane_b32 s11, v2
	v_readfirstlane_b32 s12, v3
	s_add_u32 s10, s10, 1
	s_mul_i32 s14, s13, s11
	s_cmp_eq_u32 s10, s14
	s_cbranch_scc1 .Lnb_leader_13

.LBB0_2611:
	s_cmp_lt_i32 s89, 16
	s_cbranch_scc1 .LBB0_2657
	s_waitcnt vmcnt(0) lgkmcnt(0)
	s_barrier
	v_readlane_b32 s0, v254, 0
	v_readlane_b32 s4, v254, 6
	v_readlane_b32 s5, v254, 5
	s_andn2_b32 s0, s0, 63
	s_cmp_lg_u32 s0, 0
	s_cbranch_scc1 .Lnb_end_14
	s_mov_b64 s[2:3], exec
	s_mov_b64 exec, 1
	v_mov_b32_e32 v0, s4
	v_mov_b32_e32 v4, 1
	v_mov_b32_e32 v5, 0
	ds_read_b64 v[2:3], v0
	s_lshl_b32 s6, s5, 8
	s_add_u32 s8, s84, s6
	s_addc_u32 s9, s85, 0
	s_add_u32 s16, s8, 0x2400
	s_addc_u32 s17, s9, 0
	s_add_u32 s8, s8, 0x1400
	s_addc_u32 s9, s9, 0
	s_add_u32 s20, s84, 0x3400
	s_addc_u32 s21, s85, 0
	s_add_u32 s26, s84, 0x2400
	s_addc_u32 s27, s85, 0
	s_mov_b32 s24, 0
	global_atomic_add v6, v5, v4, s[8:9] sc0
	s_add_u32 s13, s98, 1
	s_waitcnt vmcnt(0) lgkmcnt(0)
	v_readfirstlane_b32 s10, v6
	v_readfirstlane_b32 s11, v2
	v_readfirstlane_b32 s12, v3
	s_add_u32 s10, s10, 1
	s_mul_i32 s14, s13, s11
	s_cmp_eq_u32 s10, s14
	s_cbranch_scc1 .Lnb_leader_14

.LBB0_2665:
	s_cmp_lt_i32 s89, 17
	s_barrier
	s_cbranch_scc1 .LBB0_2711
	s_waitcnt vmcnt(0) lgkmcnt(0)
	s_barrier
	v_readlane_b32 s0, v254, 0
	v_readlane_b32 s4, v254, 6
	v_readlane_b32 s5, v254, 5
	s_andn2_b32 s0, s0, 63
	s_cmp_lg_u32 s0, 0
	s_cbranch_scc1 .Lnb_end_15
	s_mov_b64 s[2:3], exec
	s_mov_b64 exec, 1
	v_mov_b32_e32 v0, s4
	v_mov_b32_e32 v4, 1
	v_mov_b32_e32 v5, 0
	ds_read_b64 v[2:3], v0
	s_lshl_b32 s6, s5, 8
	s_add_u32 s8, s84, s6
	s_addc_u32 s9, s85, 0
	s_add_u32 s16, s8, 0x2400
	s_addc_u32 s17, s9, 0
	s_add_u32 s8, s8, 0x1400
	s_addc_u32 s9, s9, 0
	s_add_u32 s20, s84, 0x3400
	s_addc_u32 s21, s85, 0
	s_add_u32 s26, s84, 0x2400
	s_addc_u32 s27, s85, 0
	s_mov_b32 s24, 0
	global_atomic_add v6, v5, v4, s[8:9] sc0
	s_add_u32 s13, s98, 1
	s_waitcnt vmcnt(0) lgkmcnt(0)
	v_readfirstlane_b32 s10, v6
	v_readfirstlane_b32 s11, v2
	v_readfirstlane_b32 s12, v3
	s_add_u32 s10, s10, 1
	s_mul_i32 s14, s13, s11
	s_cmp_eq_u32 s10, s14
	s_cbranch_scc1 .Lnb_leader_15

.LBB0_2736:
	s_cmp_lt_i32 s89, 18
	s_cbranch_scc1 .LBB0_2782
	s_waitcnt vmcnt(0) lgkmcnt(0)
	s_barrier
	v_readlane_b32 s0, v254, 0
	v_readlane_b32 s4, v254, 6
	v_readlane_b32 s5, v254, 5
	s_andn2_b32 s0, s0, 63
	s_cmp_lg_u32 s0, 0
	s_cbranch_scc1 .Lnb_end_16
	s_mov_b64 s[2:3], exec
	s_mov_b64 exec, 1
	v_mov_b32_e32 v0, s4
	v_mov_b32_e32 v4, 1
	v_mov_b32_e32 v5, 0
	ds_read_b64 v[2:3], v0
	s_lshl_b32 s6, s5, 8
	s_add_u32 s8, s84, s6
	s_addc_u32 s9, s85, 0
	s_add_u32 s16, s8, 0x2400
	s_addc_u32 s17, s9, 0
	s_add_u32 s8, s8, 0x1400
	s_addc_u32 s9, s9, 0
	s_add_u32 s20, s84, 0x3400
	s_addc_u32 s21, s85, 0
	s_add_u32 s26, s84, 0x2400
	s_addc_u32 s27, s85, 0
	s_mov_b32 s24, 0
	global_atomic_add v6, v5, v4, s[8:9] sc0
	s_add_u32 s13, s98, 1
	s_waitcnt vmcnt(0) lgkmcnt(0)
	v_readfirstlane_b32 s10, v6
	v_readfirstlane_b32 s11, v2
	v_readfirstlane_b32 s12, v3
	s_add_u32 s10, s10, 1
	s_mul_i32 s14, s13, s11
	s_cmp_eq_u32 s10, s14
	s_cbranch_scc1 .Lnb_leader_16

.LBB0_2918:
	s_cmp_lt_i32 s89, 19
	s_cbranch_scc1 .LBB0_2980
	s_waitcnt vmcnt(0) lgkmcnt(0)
	s_barrier
	v_readlane_b32 s0, v254, 0
	v_readlane_b32 s4, v254, 6
	v_readlane_b32 s5, v254, 5
	s_andn2_b32 s0, s0, 63
	s_cmp_lg_u32 s0, 0
	s_cbranch_scc1 .Lnb_end_17
	s_mov_b64 s[2:3], exec
	s_mov_b64 exec, 1
	v_mov_b32_e32 v0, s4
	v_mov_b32_e32 v4, 1
	v_mov_b32_e32 v5, 0
	ds_read_b64 v[2:3], v0
	s_lshl_b32 s6, s5, 8
	s_add_u32 s8, s84, s6
	s_addc_u32 s9, s85, 0
	s_add_u32 s16, s8, 0x2400
	s_addc_u32 s17, s9, 0
	s_add_u32 s8, s8, 0x1400
	s_addc_u32 s9, s9, 0
	s_add_u32 s20, s84, 0x3400
	s_addc_u32 s21, s85, 0
	s_add_u32 s26, s84, 0x2400
	s_addc_u32 s27, s85, 0
	s_mov_b32 s24, 0
	global_atomic_add v6, v5, v4, s[8:9] sc0
	s_add_u32 s13, s98, 1
	s_waitcnt vmcnt(0) lgkmcnt(0)
	v_readfirstlane_b32 s10, v6
	v_readfirstlane_b32 s11, v2
	v_readfirstlane_b32 s12, v3
	s_add_u32 s10, s10, 1
	s_mul_i32 s14, s13, s11
	s_cmp_eq_u32 s10, s14
	s_cbranch_scc1 .Lnb_leader_17

.LBB0_2946:
	s_branch .LBB0_2895
.LBB0_2980:
	s_cmp_lt_i32 s88, 19
	s_cselect_b64 s[0:1], -1, 0
	s_cmp_gt_i32 s89, 18
	s_cselect_b64 s[2:3], -1, 0
	s_and_b64 s[0:1], s[0:1], s[2:3]
	s_andn2_b64 vcc, exec, s[0:1]
	s_cbranch_vccnz .LBB0_3034
	v_readlane_b32 s0, v254, 0
	s_waitcnt vmcnt(0)
	v_mbcnt_lo_u32_b32 v0, -1, 0
	s_andn2_b32 s0, s0, 63
	v_mbcnt_hi_u32_b32 v0, -1, v0
	v_or_b32_e32 v66, s0, v0
	v_mov_b32_e32 v0, 0
	s_mov_b32 s3, s90
	v_readlane_b32 s2, v254, 4
	v_readlane_b32 s0, v254, 3
	s_mov_b32 s1, 0
	v_readfirstlane_b32 s0, v66
	s_ashr_i32 s0, s0, 6
	s_mul_i32 s0, s0, s3
	s_add_i32 s0, s2, s0
	s_add_i32 s2, s0, 0x4000
	v_mov_b32_e32 v5, 0
	s_cmpk_gt_i32 s2, 0x441f
	s_waitcnt lgkmcnt(0)
	s_barrier
	s_barrier
	s_cbranch_scc1 .LBB0_2988
	s_load_dwordx4 s[4:7], s[92:93], 0xe0
	s_load_dwordx2 s[10:11], s[92:93], 0xc8
	v_lshlrev_b32_e32 v0, 2, v66
	v_and_b32_e32 v8, 0xfc, v0
	v_lshlrev_b32_e32 v4, 2, v8
	s_waitcnt lgkmcnt(0)
	v_mov_b32_e32 v7, s7
	v_mov_b32_e32 v6, s6
	v_lshl_add_u64 v[0:1], s[10:11], 0, v[4:5]
	s_mov_b64 s[6:7], 0x1000
	v_lshl_add_u64 v[0:1], v[0:1], 0, s[6:7]
	s_mov_b64 s[6:7], 0x300000
	v_lshlrev_b32_e32 v4, 1, v8
	s_lshl_b32 s8, s3, 3
	v_lshl_add_u64 v[2:3], v[6:7], 0, s[6:7]
	v_lshl_add_u64 v[4:5], v[6:7], 0, v[4:5]
	s_mov_b64 s[6:7], 0x1bc00000
	s_ashr_i32 s3, s2, 31
	v_lshl_add_u64 v[4:5], v[4:5], 0, s[6:7]
	s_lshl_b64 s[6:7], s[2:3], 11
	v_and_b32_e32 v9, 63, v66
	v_lshl_or_b32 v10, v9, 3, s6
	v_mov_b32_e32 v11, s7
	s_ashr_i32 s9, s8, 31
	v_lshl_add_u64 v[6:7], v[6:7], 0, v[10:11]
	s_mov_b64 s[6:7], 0x1f400000
	v_lshl_add_u64 v[6:7], v[6:7], 0, s[6:7]
	s_lshl_b64 s[6:7], s[8:9], 11
	v_mov_b32_e32 v67, 0x358637bd
	s_mov_b32 s10, 0x800000
	v_mov_b32_e32 v68, s5
	v_mov_b32_e32 v69, s4
	v_lshlrev_b32_e32 v70, 2, v8
	v_mov_b32_e32 v71, 0x3a800000
	s_branch .LBB0_2984

	.amdhsa_kernel _Z10hybrid_fwd4Args
		.amdhsa_group_segment_fixed_size 0
		.amdhsa_private_segment_fixed_size 0
		.amdhsa_kernarg_size 504
		.amdhsa_user_sgpr_count 2
		.amdhsa_user_sgpr_dispatch_ptr 0
		.amdhsa_user_sgpr_queue_ptr 0
		.amdhsa_user_sgpr_kernarg_segment_ptr 1
		.amdhsa_user_sgpr_dispatch_id 0
		.amdhsa_user_sgpr_kernarg_preload_length 0
		.amdhsa_user_sgpr_kernarg_preload_offset 0
		.amdhsa_user_sgpr_private_segment_size 0
		.amdhsa_uses_dynamic_stack 0
		.amdhsa_enable_private_segment 0
		.amdhsa_system_sgpr_workgroup_id_x 1
		.amdhsa_system_sgpr_workgroup_id_y 0
		.amdhsa_system_sgpr_workgroup_id_z 0
		.amdhsa_system_sgpr_workgroup_info 0
		.amdhsa_system_vgpr_workitem_id 0
		.amdhsa_next_free_vgpr 256
		.amdhsa_next_free_sgpr 102
		.amdhsa_accum_offset 256
		.amdhsa_reserve_vcc 1
		.amdhsa_float_round_mode_32 0
		.amdhsa_float_round_mode_16_64 0
		.amdhsa_float_denorm_mode_32 3
		.amdhsa_float_denorm_mode_16_64 3
		.amdhsa_dx10_clamp 1
		.amdhsa_ieee_mode 1
		.amdhsa_fp16_overflow 0
		.amdhsa_tg_split 0
		.amdhsa_exception_fp_ieee_invalid_op 0
		.amdhsa_exception_fp_denorm_src 0
		.amdhsa_exception_fp_ieee_div_zero 0
		.amdhsa_exception_fp_ieee_overflow 0
		.amdhsa_exception_fp_ieee_underflow 0
		.amdhsa_exception_fp_ieee_inexact 0
		.amdhsa_exception_int_div_zero 0
	.end_amdhsa_kernel

amdhsa.kernels:
  - .agpr_count:     0
    .args:
      - .offset:         0
        .size:           248
        .value_kind:     by_value
      - .offset:         248
        .size:           4
        .value_kind:     hidden_block_count_x
      - .offset:         252
        .size:           4
        .value_kind:     hidden_block_count_y
      - .offset:         256
        .size:           4
        .value_kind:     hidden_block_count_z
      - .offset:         260
        .size:           2
        .value_kind:     hidden_group_size_x
      - .offset:         262
        .size:           2
        .value_kind:     hidden_group_size_y
      - .offset:         264
        .size:           2
        .value_kind:     hidden_group_size_z
      - .offset:         266
        .size:           2
        .value_kind:     hidden_remainder_x
      - .offset:         268
        .size:           2
        .value_kind:     hidden_remainder_y
      - .offset:         270
        .size:           2
        .value_kind:     hidden_remainder_z
      - .offset:         288
        .size:           8
        .value_kind:     hidden_global_offset_x
      - .offset:         296
        .size:           8
        .value_kind:     hidden_global_offset_y
      - .offset:         304
        .size:           8
        .value_kind:     hidden_global_offset_z
      - .offset:         312
        .size:           2
        .value_kind:     hidden_grid_dims
      - .offset:         368
        .size:           4
        .value_kind:     hidden_dynamic_lds_size
    .group_segment_fixed_size: 0
    .kernarg_segment_align: 8
    .kernarg_segment_size: 504
    .language:       OpenCL C
    .language_version:
      - 2
      - 0
    .max_flat_workgroup_size: 512
    .name:           _Z10hybrid_fwd4Args
    .private_segment_fixed_size: 0
    .sgpr_count:     108
    .sgpr_spill_count: 125
    .symbol:         _Z10hybrid_fwd4Args.kd
    .uniform_work_group_size: 1
    .uses_dynamic_stack: false
    .vgpr_count:     256
    .vgpr_spill_count: 0
    .wavefront_size: 64
